# GEMM accumulator reset per unit: 64 v_mov_b64 instead of 128 v_mov_b32 (P1, P4a, P4b, P6, P7, P8)
# speedup vs baseline: 1.0149x; 1.0069x over previous
.LBB0_162:
	s_ashr_i32 s39, s38, 31
	s_lshl_b64 s[40:41], s[38:39], 19
	s_add_u32 s40, s74, s40
	s_addc_u32 s41, s75, s41
	s_and_b64 s[42:43], s[0:1], exec
	s_cselect_b32 s5, s41, s9
	s_cselect_b32 s7, s40, s8
	s_ashr_i32 s37, s36, 31
	s_lshl_b64 s[42:43], s[36:37], 19
	s_add_u32 s42, s16, s42
	s_addc_u32 s43, s17, s43
	s_and_b64 s[46:47], s[0:1], exec
	s_cselect_b32 s37, s43, s45
	s_cselect_b32 s39, s42, s44
	s_add_u32 s8, s8, 0x40080
	s_addc_u32 s9, s9, 0
	s_add_u32 s48, s44, 0x100
	s_addc_u32 s49, s45, 0
	s_mov_b32 s50, -2
	v_mov_b64_e32 v[0:1], 0
	v_mov_b64_e32 v[2:3], 0
	v_mov_b64_e32 v[4:5], 0
	v_mov_b64_e32 v[6:7], 0
	v_mov_b64_e32 v[8:9], 0
	v_mov_b64_e32 v[10:11], 0
	v_mov_b64_e32 v[12:13], 0
	v_mov_b64_e32 v[14:15], 0
	v_mov_b64_e32 v[16:17], 0
	v_mov_b64_e32 v[18:19], 0
	v_mov_b64_e32 v[20:21], 0
	v_mov_b64_e32 v[22:23], 0
	v_mov_b64_e32 v[24:25], 0
	v_mov_b64_e32 v[26:27], 0
	v_mov_b64_e32 v[28:29], 0
	v_mov_b64_e32 v[30:31], 0
	v_mov_b64_e32 v[32:33], 0
	v_mov_b64_e32 v[34:35], 0
	v_mov_b64_e32 v[36:37], 0
	v_mov_b64_e32 v[38:39], 0
	v_mov_b64_e32 v[40:41], 0
	v_mov_b64_e32 v[42:43], 0
	v_mov_b64_e32 v[44:45], 0
	v_mov_b64_e32 v[46:47], 0
	v_mov_b64_e32 v[48:49], 0
	v_mov_b64_e32 v[50:51], 0
	v_mov_b64_e32 v[52:53], 0
	v_mov_b64_e32 v[54:55], 0
	v_mov_b64_e32 v[56:57], 0
	v_mov_b64_e32 v[58:59], 0
	v_mov_b64_e32 v[60:61], 0
	v_mov_b64_e32 v[62:63], 0
	v_mov_b64_e32 v[64:65], 0
	v_mov_b64_e32 v[66:67], 0
	v_mov_b64_e32 v[68:69], 0
	v_mov_b64_e32 v[70:71], 0
	v_mov_b64_e32 v[72:73], 0
	v_mov_b64_e32 v[74:75], 0
	v_mov_b64_e32 v[76:77], 0
	v_mov_b64_e32 v[78:79], 0
	v_mov_b64_e32 v[80:81], 0
	v_mov_b64_e32 v[82:83], 0
	v_mov_b64_e32 v[84:85], 0
	v_mov_b64_e32 v[86:87], 0
	v_mov_b64_e32 v[88:89], 0
	v_mov_b64_e32 v[90:91], 0
	v_mov_b64_e32 v[92:93], 0
	v_mov_b64_e32 v[94:95], 0
	v_mov_b64_e32 v[96:97], 0
	v_mov_b64_e32 v[98:99], 0
	v_mov_b64_e32 v[100:101], 0
	v_mov_b64_e32 v[102:103], 0
	v_mov_b64_e32 v[104:105], 0
	v_mov_b64_e32 v[106:107], 0
	v_mov_b64_e32 v[108:109], 0
	v_mov_b64_e32 v[110:111], 0
	v_mov_b64_e32 v[112:113], 0
	v_mov_b64_e32 v[114:115], 0
	v_mov_b64_e32 v[116:117], 0
	v_mov_b64_e32 v[118:119], 0
	v_mov_b64_e32 v[120:121], 0
	v_mov_b64_e32 v[122:123], 0
	v_mov_b64_e32 v[124:125], 0
	v_mov_b64_e32 v[126:127], 0

.LBB0_639:
	s_ashr_i32 s13, s12, 31
	s_lshl_b64 s[16:17], s[12:13], 19
	s_add_u32 s16, s74, s16
	s_addc_u32 s17, s75, s17
	s_and_b64 s[18:19], s[38:39], exec
	s_cselect_b32 s13, s17, s37
	s_cselect_b32 s67, s16, s36
	s_ashr_i32 s11, s10, 31
	s_lshl_b64 s[18:19], s[10:11], 19
	s_add_u32 s18, s15, s18
	s_addc_u32 s19, s20, s19
	s_and_b64 s[46:47], s[38:39], exec
	s_cselect_b32 s11, s19, s43
	s_cselect_b32 s68, s18, s42
	s_add_u32 s36, s36, 0x40080
	s_addc_u32 s37, s37, 0
	s_add_u32 s69, s42, 0x100
	s_addc_u32 s70, s43, 0
	s_mov_b32 s71, -2
	v_mov_b64_e32 v[0:1], 0
	v_mov_b64_e32 v[2:3], 0
	v_mov_b64_e32 v[4:5], 0
	v_mov_b64_e32 v[6:7], 0
	v_mov_b64_e32 v[8:9], 0
	v_mov_b64_e32 v[10:11], 0
	v_mov_b64_e32 v[12:13], 0
	v_mov_b64_e32 v[14:15], 0
	v_mov_b64_e32 v[16:17], 0
	v_mov_b64_e32 v[18:19], 0
	v_mov_b64_e32 v[20:21], 0
	v_mov_b64_e32 v[22:23], 0
	v_mov_b64_e32 v[24:25], 0
	v_mov_b64_e32 v[26:27], 0
	v_mov_b64_e32 v[28:29], 0
	v_mov_b64_e32 v[30:31], 0
	v_mov_b64_e32 v[32:33], 0
	v_mov_b64_e32 v[34:35], 0
	v_mov_b64_e32 v[36:37], 0
	v_mov_b64_e32 v[38:39], 0
	v_mov_b64_e32 v[40:41], 0
	v_mov_b64_e32 v[42:43], 0
	v_mov_b64_e32 v[44:45], 0
	v_mov_b64_e32 v[46:47], 0
	v_mov_b64_e32 v[48:49], 0
	v_mov_b64_e32 v[50:51], 0
	v_mov_b64_e32 v[52:53], 0
	v_mov_b64_e32 v[54:55], 0
	v_mov_b64_e32 v[56:57], 0
	v_mov_b64_e32 v[58:59], 0
	v_mov_b64_e32 v[60:61], 0
	v_mov_b64_e32 v[62:63], 0
	v_mov_b64_e32 v[64:65], 0
	v_mov_b64_e32 v[66:67], 0
	v_mov_b64_e32 v[68:69], 0
	v_mov_b64_e32 v[70:71], 0
	v_mov_b64_e32 v[72:73], 0
	v_mov_b64_e32 v[74:75], 0
	v_mov_b64_e32 v[76:77], 0
	v_mov_b64_e32 v[78:79], 0
	v_mov_b64_e32 v[80:81], 0
	v_mov_b64_e32 v[82:83], 0
	v_mov_b64_e32 v[84:85], 0
	v_mov_b64_e32 v[86:87], 0
	v_mov_b64_e32 v[88:89], 0
	v_mov_b64_e32 v[90:91], 0
	v_mov_b64_e32 v[92:93], 0
	v_mov_b64_e32 v[94:95], 0
	v_mov_b64_e32 v[96:97], 0
	v_mov_b64_e32 v[98:99], 0
	v_mov_b64_e32 v[100:101], 0
	v_mov_b64_e32 v[102:103], 0
	v_mov_b64_e32 v[104:105], 0
	v_mov_b64_e32 v[106:107], 0
	v_mov_b64_e32 v[108:109], 0
	v_mov_b64_e32 v[110:111], 0
	v_mov_b64_e32 v[112:113], 0
	v_mov_b64_e32 v[114:115], 0
	v_mov_b64_e32 v[116:117], 0
	v_mov_b64_e32 v[118:119], 0
	v_mov_b64_e32 v[120:121], 0
	v_mov_b64_e32 v[122:123], 0
	v_mov_b64_e32 v[124:125], 0
	v_mov_b64_e32 v[126:127], 0

.LBB0_676:
	s_ashr_i32 s13, s12, 31
	s_lshl_b64 s[16:17], s[12:13], 19
	s_add_u32 s16, s15, s16
	s_addc_u32 s17, s20, s17
	s_and_b64 s[18:19], s[38:39], exec
	s_cselect_b32 s13, s17, s37
	s_cselect_b32 s53, s16, s36
	s_ashr_i32 s11, s10, 31
	s_lshl_b64 s[18:19], s[10:11], 19
	s_add_u32 s18, s74, s18
	s_addc_u32 s19, s75, s19
	s_and_b64 s[46:47], s[38:39], exec
	s_cselect_b32 s11, s19, s43
	s_cselect_b32 s64, s18, s42
	s_add_u32 s36, s36, 0x40080
	s_addc_u32 s37, s37, 0
	s_add_u32 s65, s42, 0x100
	s_addc_u32 s66, s43, 0
	s_mov_b32 s67, -2
	v_mov_b64_e32 v[0:1], 0
	v_mov_b64_e32 v[2:3], 0
	v_mov_b64_e32 v[4:5], 0
	v_mov_b64_e32 v[6:7], 0
	v_mov_b64_e32 v[8:9], 0
	v_mov_b64_e32 v[10:11], 0
	v_mov_b64_e32 v[12:13], 0
	v_mov_b64_e32 v[14:15], 0
	v_mov_b64_e32 v[16:17], 0
	v_mov_b64_e32 v[18:19], 0
	v_mov_b64_e32 v[20:21], 0
	v_mov_b64_e32 v[22:23], 0
	v_mov_b64_e32 v[24:25], 0
	v_mov_b64_e32 v[26:27], 0
	v_mov_b64_e32 v[28:29], 0
	v_mov_b64_e32 v[30:31], 0
	v_mov_b64_e32 v[32:33], 0
	v_mov_b64_e32 v[34:35], 0
	v_mov_b64_e32 v[36:37], 0
	v_mov_b64_e32 v[38:39], 0
	v_mov_b64_e32 v[40:41], 0
	v_mov_b64_e32 v[42:43], 0
	v_mov_b64_e32 v[44:45], 0
	v_mov_b64_e32 v[46:47], 0
	v_mov_b64_e32 v[48:49], 0
	v_mov_b64_e32 v[50:51], 0
	v_mov_b64_e32 v[52:53], 0
	v_mov_b64_e32 v[54:55], 0
	v_mov_b64_e32 v[56:57], 0
	v_mov_b64_e32 v[58:59], 0
	v_mov_b64_e32 v[60:61], 0
	v_mov_b64_e32 v[62:63], 0
	v_mov_b64_e32 v[64:65], 0
	v_mov_b64_e32 v[66:67], 0
	v_mov_b64_e32 v[68:69], 0
	v_mov_b64_e32 v[70:71], 0
	v_mov_b64_e32 v[72:73], 0
	v_mov_b64_e32 v[74:75], 0
	v_mov_b64_e32 v[76:77], 0
	v_mov_b64_e32 v[78:79], 0
	v_mov_b64_e32 v[80:81], 0
	v_mov_b64_e32 v[82:83], 0
	v_mov_b64_e32 v[84:85], 0
	v_mov_b64_e32 v[86:87], 0
	v_mov_b64_e32 v[88:89], 0
	v_mov_b64_e32 v[90:91], 0
	v_mov_b64_e32 v[92:93], 0
	v_mov_b64_e32 v[94:95], 0
	v_mov_b64_e32 v[96:97], 0
	v_mov_b64_e32 v[98:99], 0
	v_mov_b64_e32 v[100:101], 0
	v_mov_b64_e32 v[102:103], 0
	v_mov_b64_e32 v[104:105], 0
	v_mov_b64_e32 v[106:107], 0
	v_mov_b64_e32 v[108:109], 0
	v_mov_b64_e32 v[110:111], 0
	v_mov_b64_e32 v[112:113], 0
	v_mov_b64_e32 v[114:115], 0
	v_mov_b64_e32 v[116:117], 0
	v_mov_b64_e32 v[118:119], 0
	v_mov_b64_e32 v[120:121], 0
	v_mov_b64_e32 v[122:123], 0
	v_mov_b64_e32 v[124:125], 0
	v_mov_b64_e32 v[126:127], 0

.LBB0_884:
	s_ashr_i32 s17, s16, 31
	s_lshl_b64 s[18:19], s[16:17], 19
	s_add_u32 s18, s28, s18
	s_addc_u32 s19, s29, s19
	s_and_b64 s[24:25], s[42:43], exec
	s_cselect_b32 s17, s19, s31
	s_cselect_b32 s27, s18, s30
	s_ashr_i32 s13, s12, 31
	s_lshl_b64 s[24:25], s[12:13], 19
	s_add_u32 s24, s60, s24
	s_addc_u32 s25, s61, s25
	s_and_b64 s[36:37], s[42:43], exec
	s_cselect_b32 s13, s25, s35
	s_cselect_b32 s50, s24, s34
	s_add_u32 s30, s30, 0x40080
	s_addc_u32 s31, s31, 0
	s_add_u32 s51, s34, 0x100
	s_addc_u32 s52, s35, 0
	s_mov_b32 s53, -2
	s_waitcnt lgkmcnt(0)
	v_mov_b64_e32 v[0:1], 0
	v_mov_b64_e32 v[2:3], 0
	v_mov_b64_e32 v[4:5], 0
	v_mov_b64_e32 v[6:7], 0
	v_mov_b64_e32 v[8:9], 0
	v_mov_b64_e32 v[10:11], 0
	v_mov_b64_e32 v[12:13], 0
	v_mov_b64_e32 v[14:15], 0
	v_mov_b64_e32 v[16:17], 0
	v_mov_b64_e32 v[18:19], 0
	v_mov_b64_e32 v[20:21], 0
	v_mov_b64_e32 v[22:23], 0
	v_mov_b64_e32 v[24:25], 0
	v_mov_b64_e32 v[26:27], 0
	v_mov_b64_e32 v[28:29], 0
	v_mov_b64_e32 v[30:31], 0
	v_mov_b64_e32 v[32:33], 0
	v_mov_b64_e32 v[34:35], 0
	v_mov_b64_e32 v[36:37], 0
	v_mov_b64_e32 v[38:39], 0
	v_mov_b64_e32 v[40:41], 0
	v_mov_b64_e32 v[42:43], 0
	v_mov_b64_e32 v[44:45], 0
	v_mov_b64_e32 v[46:47], 0
	v_mov_b64_e32 v[48:49], 0
	v_mov_b64_e32 v[50:51], 0
	v_mov_b64_e32 v[52:53], 0
	v_mov_b64_e32 v[54:55], 0
	v_mov_b64_e32 v[56:57], 0
	v_mov_b64_e32 v[58:59], 0
	v_mov_b64_e32 v[60:61], 0
	v_mov_b64_e32 v[62:63], 0
	v_mov_b64_e32 v[64:65], 0
	v_mov_b64_e32 v[66:67], 0
	v_mov_b64_e32 v[68:69], 0
	v_mov_b64_e32 v[70:71], 0
	v_mov_b64_e32 v[72:73], 0
	v_mov_b64_e32 v[74:75], 0
	v_mov_b64_e32 v[76:77], 0
	v_mov_b64_e32 v[78:79], 0
	v_mov_b64_e32 v[80:81], 0
	v_mov_b64_e32 v[82:83], 0
	v_mov_b64_e32 v[84:85], 0
	v_mov_b64_e32 v[86:87], 0
	v_mov_b64_e32 v[88:89], 0
	v_mov_b64_e32 v[90:91], 0
	v_mov_b64_e32 v[92:93], 0
	v_mov_b64_e32 v[94:95], 0
	v_mov_b64_e32 v[96:97], 0
	v_mov_b64_e32 v[98:99], 0
	v_mov_b64_e32 v[100:101], 0
	v_mov_b64_e32 v[102:103], 0
	v_mov_b64_e32 v[104:105], 0
	v_mov_b64_e32 v[106:107], 0
	v_mov_b64_e32 v[108:109], 0
	v_mov_b64_e32 v[110:111], 0
	v_mov_b64_e32 v[112:113], 0
	v_mov_b64_e32 v[114:115], 0
	v_mov_b64_e32 v[116:117], 0
	v_mov_b64_e32 v[118:119], 0
	v_mov_b64_e32 v[120:121], 0
	v_mov_b64_e32 v[122:123], 0
	v_mov_b64_e32 v[124:125], 0
	v_mov_b64_e32 v[126:127], 0

.LBB0_973:
	s_ashr_i32 s17, s16, 31
	s_lshl_b64 s[18:19], s[16:17], 19
	s_add_u32 s18, s82, s18
	s_addc_u32 s19, s83, s19
	s_and_b64 s[20:21], s[40:41], exec
	s_cselect_b32 s17, s19, s27
	s_cselect_b32 s47, s18, s26
	s_ashr_i32 s13, s12, 31
	s_lshl_b64 s[20:21], s[12:13], 19
	s_add_u32 s20, s58, s20
	s_addc_u32 s21, s59, s21
	s_and_b64 s[30:31], s[40:41], exec
	s_cselect_b32 s13, s21, s29
	s_cselect_b32 s48, s20, s28
	s_add_u32 s26, s26, 0x40080
	s_addc_u32 s27, s27, 0
	s_add_u32 s49, s28, 0x100
	s_addc_u32 s50, s29, 0
	s_mov_b32 s51, -2
	v_mov_b64_e32 v[0:1], 0
	v_mov_b64_e32 v[2:3], 0
	v_mov_b64_e32 v[4:5], 0
	v_mov_b64_e32 v[6:7], 0
	v_mov_b64_e32 v[8:9], 0
	v_mov_b64_e32 v[10:11], 0
	v_mov_b64_e32 v[12:13], 0
	v_mov_b64_e32 v[14:15], 0
	v_mov_b64_e32 v[16:17], 0
	v_mov_b64_e32 v[18:19], 0
	v_mov_b64_e32 v[20:21], 0
	v_mov_b64_e32 v[22:23], 0
	v_mov_b64_e32 v[24:25], 0
	v_mov_b64_e32 v[26:27], 0
	v_mov_b64_e32 v[28:29], 0
	v_mov_b64_e32 v[30:31], 0
	v_mov_b64_e32 v[32:33], 0
	v_mov_b64_e32 v[34:35], 0
	v_mov_b64_e32 v[36:37], 0
	v_mov_b64_e32 v[38:39], 0
	v_mov_b64_e32 v[40:41], 0
	v_mov_b64_e32 v[42:43], 0
	v_mov_b64_e32 v[44:45], 0
	v_mov_b64_e32 v[46:47], 0
	v_mov_b64_e32 v[48:49], 0
	v_mov_b64_e32 v[50:51], 0
	v_mov_b64_e32 v[52:53], 0
	v_mov_b64_e32 v[54:55], 0
	v_mov_b64_e32 v[56:57], 0
	v_mov_b64_e32 v[58:59], 0
	v_mov_b64_e32 v[60:61], 0
	v_mov_b64_e32 v[62:63], 0
	v_mov_b64_e32 v[64:65], 0
	v_mov_b64_e32 v[66:67], 0
	v_mov_b64_e32 v[68:69], 0
	v_mov_b64_e32 v[70:71], 0
	v_mov_b64_e32 v[72:73], 0
	v_mov_b64_e32 v[74:75], 0
	v_mov_b64_e32 v[76:77], 0
	v_mov_b64_e32 v[78:79], 0
	v_mov_b64_e32 v[80:81], 0
	v_mov_b64_e32 v[82:83], 0
	v_mov_b64_e32 v[84:85], 0
	v_mov_b64_e32 v[86:87], 0
	v_mov_b64_e32 v[88:89], 0
	v_mov_b64_e32 v[90:91], 0
	v_mov_b64_e32 v[92:93], 0
	v_mov_b64_e32 v[94:95], 0
	v_mov_b64_e32 v[96:97], 0
	v_mov_b64_e32 v[98:99], 0
	v_mov_b64_e32 v[100:101], 0
	v_mov_b64_e32 v[102:103], 0
	v_mov_b64_e32 v[104:105], 0
	v_mov_b64_e32 v[106:107], 0
	v_mov_b64_e32 v[108:109], 0
	v_mov_b64_e32 v[110:111], 0
	v_mov_b64_e32 v[112:113], 0
	v_mov_b64_e32 v[114:115], 0
	v_mov_b64_e32 v[116:117], 0
	v_mov_b64_e32 v[118:119], 0
	v_mov_b64_e32 v[120:121], 0
	v_mov_b64_e32 v[122:123], 0
	v_mov_b64_e32 v[124:125], 0
	v_mov_b64_e32 v[126:127], 0

.LBB0_1054:
	s_add_u32 s37, s16, 0x100
	s_addc_u32 s38, s17, 0
	s_mov_b32 s39, -2
	v_mov_b64_e32 v[0:1], 0
	v_mov_b64_e32 v[2:3], 0
	v_mov_b64_e32 v[4:5], 0
	v_mov_b64_e32 v[6:7], 0
	v_mov_b64_e32 v[8:9], 0
	v_mov_b64_e32 v[10:11], 0
	v_mov_b64_e32 v[12:13], 0
	v_mov_b64_e32 v[14:15], 0
	v_mov_b64_e32 v[16:17], 0
	v_mov_b64_e32 v[18:19], 0
	v_mov_b64_e32 v[20:21], 0
	v_mov_b64_e32 v[22:23], 0
	v_mov_b64_e32 v[24:25], 0
	v_mov_b64_e32 v[26:27], 0
	v_mov_b64_e32 v[28:29], 0
	v_mov_b64_e32 v[30:31], 0
	v_mov_b64_e32 v[32:33], 0
	v_mov_b64_e32 v[34:35], 0
	v_mov_b64_e32 v[36:37], 0
	v_mov_b64_e32 v[38:39], 0
	v_mov_b64_e32 v[40:41], 0
	v_mov_b64_e32 v[42:43], 0
	v_mov_b64_e32 v[44:45], 0
	v_mov_b64_e32 v[46:47], 0
	v_mov_b64_e32 v[48:49], 0
	v_mov_b64_e32 v[50:51], 0
	v_mov_b64_e32 v[52:53], 0
	v_mov_b64_e32 v[54:55], 0
	v_mov_b64_e32 v[56:57], 0
	v_mov_b64_e32 v[58:59], 0
	v_mov_b64_e32 v[60:61], 0
	v_mov_b64_e32 v[62:63], 0
	v_mov_b64_e32 v[64:65], 0
	v_mov_b64_e32 v[66:67], 0
	v_mov_b64_e32 v[68:69], 0
	v_mov_b64_e32 v[70:71], 0
	v_mov_b64_e32 v[72:73], 0
	v_mov_b64_e32 v[74:75], 0
	v_mov_b64_e32 v[76:77], 0
	v_mov_b64_e32 v[78:79], 0
	v_mov_b64_e32 v[80:81], 0
	v_mov_b64_e32 v[82:83], 0
	v_mov_b64_e32 v[84:85], 0
	v_mov_b64_e32 v[86:87], 0
	v_mov_b64_e32 v[88:89], 0
	v_mov_b64_e32 v[90:91], 0
	v_mov_b64_e32 v[92:93], 0
	v_mov_b64_e32 v[94:95], 0
	v_mov_b64_e32 v[96:97], 0
	v_mov_b64_e32 v[98:99], 0
	v_mov_b64_e32 v[100:101], 0
	v_mov_b64_e32 v[102:103], 0
	v_mov_b64_e32 v[104:105], 0
	v_mov_b64_e32 v[106:107], 0
	v_mov_b64_e32 v[108:109], 0
	v_mov_b64_e32 v[110:111], 0
	v_mov_b64_e32 v[112:113], 0
	v_mov_b64_e32 v[114:115], 0
	v_mov_b64_e32 v[116:117], 0
	v_mov_b64_e32 v[118:119], 0
	v_mov_b64_e32 v[120:121], 0
	v_mov_b64_e32 v[122:123], 0
	v_mov_b64_e32 v[124:125], 0
	v_mov_b64_e32 v[126:127], 0
